# speedup vs baseline: 1.0046x; 1.0046x over previous
; #define LAS __attribute__((address_space(3)))
; #define SREP(bit) for (int rep_ = 0; rep_ < (((SUBDUP >> (bit)) & 1) ? 2 : 1); ++rep_)
; __device__ __forceinline__ void rw_scan4(const int tid, LAS float* lds, const float* RW, int task, int ntasks, int mode, const float* SIN, float* PQ, float* Y) {
;     const int slot = tid >> 7, sl = tid & 127, kp = sl & 7, rg = sl >> 3;
;     const bool active = task < ntasks;
;     int head = 0, c = 0, kind = 2;
;     if (active) { if (mode == 0) { kind = task & 1; head = (task >> 1) & 7; c = task >> 4; } else { head = task & 7; c = task >> 3; } }
;     const int t0 = c * CHL;
;     f32x2 s[4][4];
;     if (kind == 2 && active) {
;         const float* ip = SIN + (size_t)(head * NCH + c) * 4096 + (rg * 4) * 64 + kp * 8;
; #pragma unroll
;         for (int j = 0; j < 4; ++j) { const f32x4 i0 = *(const f32x4*)(ip + j * 64), i1 = *(const f32x4*)(ip + j * 64 + 4);
;             s[j][0] = (f32x2){i0.x, i0.y}; s[j][1] = (f32x2){i0.z, i0.w}; s[j][2] = (f32x2){i1.x, i1.y}; s[j][3] = (f32x2){i1.z, i1.w}; }
;     } else {
; #pragma unroll
;         for (int j = 0; j < 4; ++j)
; #pragma unroll
;             for (int i = 0; i < 4; ++i) { const int kk = kp * 8 + 2 * i, rr = rg * 4 + j; s[j][i] = (f32x2){(kind == 1 && kk == rr) ? 1.f : 0.f, (kind == 1 && kk + 1 == rr) ? 1.f : 0.f}; }
;     }
;     LAS float* sb = lds + slot * (2 * 6 * TB * 64);
;     const int srow = sl >> 4, sc4 = sl & 15;
;     const float* gsrc = RW + (size_t)(t0 + srow) * GW + head * 64 + sc4 * 4;
;     f32x4 st[6];
; __global__ void __launch_bounds__(NTHR, 2) hymba_fwd(Args args) {
;     ...
;             SREP(4) for (int tb = 0; tb < NCH * 8 * 2; tb += 4 * G) rw_scan4(tid, ldsf, WSP(float, WS_RW), tb + bid * 4 + (tid >> 7), NCH * 8 * 2, 0, nullptr, WSP(float, WS_PQ), nullptr);
.LBB0_210:
	v_readlane_b32 s0, v254, 29
	s_cmp_gt_i32 s0, 4
	s_mov_b64 s[0:1], -1
	s_cbranch_scc0 .LBB0_347
	v_readlane_b32 s0, v254, 29
	s_cmp_gt_i32 s0, 5
	s_mov_b64 s[0:1], -1
	s_cbranch_scc0 .LBB0_314
	v_readlane_b32 s0, v254, 44
	s_cmp_lt_u32 s0, 4
	s_cbranch_scc0 .Lp6_prio_done
	s_setprio 1
.Lp6_prio_done:
	s_waitcnt vmcnt(5)
	v_and_b32_e32 v1, 7, v148
	s_waitcnt vmcnt(4)
	v_bfe_u32 v6, v148, 3, 4
	v_ashrrev_i32_e32 v0, 7, v148
	v_lshlrev_b32_e32 v2, 3, v1
	v_lshlrev_b32_e32 v3, 2, v6
	s_movk_i32 s4, 0x6000
	v_lshlrev_b32_e32 v130, 2, v148
	v_and_b32_e32 v131, 1, v0
	v_lshrrev_b32_e32 v132, 1, v0
	v_lshlrev_b32_e32 v131, 1, v131
	v_or_b32_e32 v131, v131, v132
	v_lshl_add_u32 v131, s44, 2, v131
	v_cmp_eq_u32_e64 s[38:39], v2, v3
	v_or_b32_e32 v2, 4, v2
	v_mul_lo_u32 v7, v0, s4
	v_bfe_u32 v133, v148, 4, 3
	v_and_b32_e32 v0, 60, v130
	v_readlane_b32 s0, v254, 32
	v_cmp_eq_u32_e64 s[40:41], v2, v3
	v_add_u32_e32 v3, 0, v7
	v_lshlrev_b32_e32 v4, 2, v0
	v_lshlrev_b32_e32 v2, 5, v1
	v_lshlrev_b32_e32 v1, 8, v133
	v_readlane_b32 s1, v254, 33
	v_add3_u32 v134, v3, v4, v1
	v_lshlrev_b32_e32 v4, 10, v6
	v_mov_b32_e32 v5, v144
	s_load_dwordx16 s[48:63], s[0:1], 0x38
	s_waitcnt lgkmcnt(0)
	v_lshl_add_u64 v[4:5], s[18:19], 0, v[4:5]
	v_mov_b32_e32 v3, v144
	v_lshl_add_u64 v[4:5], v[4:5], 0, v[2:3]
	s_mov_b64 s[4:5], 0x28300000
	s_add_u32 s0, s18, 0x16200000
	v_lshl_add_u64 v[92:93], v[4:5], 0, s[4:5]
	v_lshl_or_b32 v1, v6, 4, v7
	v_readlane_b32 s4, v254, 15
	s_addc_u32 s1, s19, 0
	s_lshl_b32 s14, s45, 2
	v_add_u32_e32 v135, s4, v1
	v_or_b32_e32 v1, v7, v2
	s_add_i32 s4, 0, 0x800
	v_cmp_eq_u32_e64 s[42:43], 1, v132
	v_add_u32_e32 v136, s4, v1
	s_mov_b32 s15, 0
	v_lshlrev_b32_e32 v94, 2, v0
	s_branch .LBB0_214

; #define LAS __attribute__((address_space(3)))
; #define SREP(bit) for (int rep_ = 0; rep_ < (((SUBDUP >> (bit)) & 1) ? 2 : 1); ++rep_)
; template <bool SECOND>
; __device__ __forceinline__ void s5_unit(const int tid, LAS float* ldsf, const float* P, const LayerP& L, f32x2* E, float* VF, bf16* VB, int unit) {
;     const int lane = tid & 63, wave = tid >> 6;
;     const int g = unit >> 4, chunk = (unit & 15) * 8 + wave, n = lane, t0 = chunk * 64;
;     LAS float* CT = ldsf;
;     LAS float* uT = ldsf + 16 * 132 + wave * (1024 + 2112);
;     LAS float* sT = uT + 1024;
;     const float lr = L.s5_lre[g * 64 + n], li = L.s5_lim[g * 64 + n], dt = expf(L.s5_ldt[g]);
;     const float mag = expf(lr * dt), ar = mag * cosf(li * dt), ai = mag * sinf(li * dt);
;     const float den = lr * lr + li * li, gre = ((ar - 1.f) * lr + ai * li) / den, gim = (ai * lr - (ar - 1.f) * li) / den;
;     float bbr[16], bbi[16];
;     f32x4 bl[8], ut[4]; float cv[4] = {0.f, 0.f, 0.f, 0.f};
; __global__ void __launch_bounds__(NTHR, 2) hymba_fwd(Args args) {
;     ...
;             SREP(5) for (int u = bid; u < 32 * 16; u += G) s5_unit<true>(tid, ldsf, P, L, WSP(f32x2, WS_E), WSP(float, WS_VF), WSP(bf16, WS_VB), u);
.LBB0_251:
	s_setprio 0
	v_readlane_b32 s0, v254, 39
	s_cmpk_gt_i32 s0, 0x1ff
	s_barrier
	s_cbranch_scc1 .LBB0_306
	v_readlane_b32 s0, v254, 30
	v_readlane_b32 s1, v254, 31
	s_mov_b32 s10, s0
	s_ashr_i32 s11, s0, 31
	s_lshl_b64 s[8:9], s[10:11], 7
	s_lshl_b64 s[0:1], s[10:11], 11
	s_lshl_b64 s[6:7], s[10:11], 13
	s_add_u32 s4, s48, s6
	s_addc_u32 s5, s49, s7
	s_add_u32 s6, s50, s6
	s_addc_u32 s7, s51, s7
	s_add_u32 s12, s52, s8
	s_mov_b32 s8, s10
	s_addc_u32 s29, s53, s9
	v_writelane_b32 v254, s8, 30
	s_lshl_b64 s[14:15], s[10:11], 17
	s_waitcnt vmcnt(5)
	v_lshlrev_b32_e32 v0, 2, v130
	v_writelane_b32 v254, s9, 31
	s_add_u32 s8, s54, s14
	s_addc_u32 s9, s55, s15
	s_add_u32 s10, s56, s14
	s_addc_u32 s11, s57, s15
	s_add_u32 s24, s58, s14
	s_addc_u32 s25, s59, s15
	s_add_u32 s26, s60, s14
	v_ashrrev_i32_e32 v51, 6, v148
	s_movk_i32 s14, 0x3100
	v_and_b32_e32 v0, 48, v0
	v_mov_b32_e32 v1, v144
	s_addc_u32 s27, s61, s15
	s_waitcnt vmcnt(4)
	v_mul_lo_u32 v6, v51, s14
	v_lshl_add_u64 v[2:3], s[18:19], 0, v[0:1]
	s_mov_b64 s[14:15], 0xc200000
	v_lshl_add_u64 v[40:41], v[2:3], 0, s[14:15]
	s_movk_i32 s15, 0x400
	v_mov_b32_e32 v1, s27
	v_mov_b32_e32 v7, s25
	v_cmp_gt_u32_e64 s[38:39], s15, v148
	s_waitcnt vmcnt(3)
	v_mov_b32_e32 v8, s26
	v_mov_b32_e32 v9, s24
	v_add_u32_e32 v10, 0x200, v148
	v_cndmask_b32_e64 v3, v1, v7, s[38:39]
	v_cndmask_b32_e64 v2, v8, v9, s[38:39]
	v_lshlrev_b32_e32 v4, 2, v188
	v_mov_b32_e32 v5, v144
	v_cmp_gt_u32_e64 s[40:41], s15, v10
	s_movk_i32 s14, 0xfbff
	v_lshl_add_u64 v[42:43], v[2:3], 0, v[4:5]
	v_cndmask_b32_e64 v3, v1, v7, s[40:41]
	v_cndmask_b32_e64 v2, v8, v9, s[40:41]
	v_cmp_lt_u32_e64 s[42:43], s14, v148
	s_waitcnt vmcnt(2)
	v_add_u32_e32 v12, 0x600, v148
	v_lshl_add_u64 v[44:45], v[2:3], 0, v[4:5]
	v_cndmask_b32_e64 v3, v1, v7, s[42:43]
	v_cndmask_b32_e64 v2, v8, v9, s[42:43]
	v_cmp_gt_u32_e64 s[44:45], s15, v12
	v_lshl_add_u64 v[46:47], v[2:3], 0, v[4:5]
	v_bfe_u32 v104, v148, 6, 4
	v_cndmask_b32_e64 v3, v1, v7, s[44:45]
	v_lshlrev_b32_e32 v1, 3, v148
	v_and_b32_e32 v1, 0x1f8, v1
	v_cndmask_b32_e64 v2, v8, v9, s[44:45]
	v_add_u32_e32 v1, 0, v1
	s_movk_i32 s14, 0x210
	v_lshl_add_u64 v[48:49], v[2:3], 0, v[4:5]
	v_ashrrev_i32_e32 v2, 10, v148
	v_mad_u32_u24 v3, v104, s14, v1
	v_bfe_u32 v105, v10, 6, 4
	v_lshl_add_u32 v107, v2, 2, v3
	v_ashrrev_i32_e32 v2, 10, v10
	v_add_u32_e32 v11, 0x400, v148
	v_mul_u32_u24_e32 v4, 0x210, v105
	v_lshlrev_b32_e32 v2, 2, v2
	v_add3_u32 v108, v1, v4, v2
	v_ashrrev_i32_e32 v2, 10, v11
	v_bfe_u32 v106, v12, 6, 4
	v_lshl_add_u32 v109, v2, 2, v3
	v_ashrrev_i32_e32 v2, 10, v12
	s_add_u32 s20, s18, 0x22200000
	v_mul_u32_u24_e32 v3, 0x210, v106
	v_lshlrev_b32_e32 v2, 2, v2
	s_addc_u32 s21, s19, 0
	v_add3_u32 v110, v1, v3, v2
	v_lshlrev_b32_e32 v1, 4, v188
	s_add_u32 s22, s18, 0x23200000
	v_add_u32_e32 v102, 0, v6
	v_and_b32_e32 v1, 0x3c0, v1
	s_addc_u32 s23, s19, 0
	v_add3_u32 v111, v102, v1, v0
	v_lshrrev_b32_e32 v0, 2, v148
	v_and_b32_e32 v7, 12, v0
	v_and_b32_e32 v0, 1, v148
	v_lshlrev_b32_e32 v52, 3, v188
	s_add_u32 s84, s62, s0
	v_mov_b32_e32 v53, v144
	v_cmp_eq_u32_e64 s[46:47], 0, v0
	s_addc_u32 s85, s63, s1
	v_lshl_add_u64 v[0:1], s[18:19], 0, v[52:53]
	s_mov_b64 s[0:1], 0x25a01e00
	v_and_b32_e32 v50, 15, v148
	v_lshl_add_u64 v[54:55], v[0:1], 0, s[0:1]
	s_movk_i32 s0, 0xffc0
	v_lshlrev_b32_e32 v0, 4, v148
	v_mul_u32_u24_e32 v2, 0x210, v50
	v_mad_u32_u24 v3, v50, s14, 0
	v_and_b32_e32 v4, 48, v148
	v_mad_u32_u24 v5, v50, s14, v102
	v_mul_i32_i24_e32 v8, 0xfffffdf4, v50
	v_and_or_b32 v53, v148, s0, v7
	v_and_b32_e32 v0, 0x300, v0
	v_readlane_b32 s0, v254, 16
	v_lshrrev_b32_e32 v103, 2, v188
	v_add3_u32 v112, v2, v8, v0
	v_add_u32_e32 v113, s0, v6
	v_add_u32_e32 v114, v3, v4
	v_add_u32_e32 v115, v5, v4
	v_readlane_b32 s30, v254, 39
	s_branch .LBB0_254
